# in-proj epilogue rotary columns: second row step of each pair reuses the cos/sin values of the first instead of reloading and waiting (8 fewer load round trips per tile)
# speedup vs baseline: 1.0007x; 1.0007x over previous
;     __device__ __forceinline__ void operator()(const f32x4 (&acc)[2][2][4][2], const Unit& u, int wr, int wc, int fr, int fq) const {
;     ...
;                         const int j0 = (col & 63) >> 1;
;                         const f32x4* cs = (const f32x4*)(rope + ((size_t)pos * 32 + j0) * 2);
;                         const f32x4 a = cs[0], b = cs[1];
;                         f32x4 w0, w1;
;                         w0[0] = v0[0] * a[0] - v0[1] * a[1]; w0[1] = v0[1] * a[0] + v0[0] * a[1];
;                         w0[2] = v0[2] * a[2] - v0[3] * a[3]; w0[3] = v0[3] * a[2] + v0[2] * a[3];
;                         w1[0] = v1[0] * b[0] - v1[1] * b[1]; w1[1] = v1[1] * b[0] + v1[0] * b[1];
;                         w1[2] = v1[2] * b[2] - v1[3] * b[3]; w1[3] = v1[3] * b[2] + v1[2] * b[3];
;                         v0 = w0; v1 = w1;
.LBB0_242:
	v_bitop3_b32 v0, s63, v220, v115 bitop3:0xc8
	s_andn2_b64 vcc, exec, s[0:1]
	v_lshl_or_b32 v145, v0, 6, v160
	s_cbranch_vccnz .LBB0_246
	s_cmp_eq_u32 s61, 1
	s_cbranch_scc0 .LBB0_245
	v_lshlrev_b32_e32 v149, 2, v145
	global_load_dwordx4 v[150:153], v149, s[50:51] offset:16
	global_load_dwordx4 v[154:157], v149, s[50:51]
	s_waitcnt vmcnt(1)
	v_pk_mul_f32 v[168:169], v[124:125], v[150:151] op_sel:[1,1] op_sel_hi:[0,1]
	s_waitcnt vmcnt(0)
	v_mov_b32_e32 v232, v150
	v_mov_b32_e32 v233, v151
	v_mov_b32_e32 v234, v152
	v_mov_b32_e32 v235, v153
	v_mov_b32_e32 v236, v154
	v_mov_b32_e32 v237, v155
	v_mov_b32_e32 v238, v156
	v_mov_b32_e32 v239, v157
	v_pk_mul_f32 v[166:167], v[128:129], v[154:155] op_sel:[1,1] op_sel_hi:[0,1]
	v_pk_mul_f32 v[164:165], v[128:129], v[154:155]
	v_pk_fma_f32 v[128:129], v[128:129], v[154:155], v[166:167] op_sel_hi:[1,0,1]
	s_nop 0
	v_mul_f32_e32 v128, v131, v157
	v_pk_fma_f32 v[154:155], v[130:131], v[156:157], v[128:129] op_sel_hi:[1,1,0] neg_lo:[0,0,1] neg_hi:[0,0,1]
	v_mul_f32_e32 v128, v130, v157
	v_pk_fma_f32 v[130:131], v[130:131], v[156:157], v[128:129] op_sel:[1,0,0] op_sel_hi:[0,1,0]
	v_pk_mul_f32 v[156:157], v[124:125], v[150:151]
	v_pk_fma_f32 v[124:125], v[124:125], v[150:151], v[168:169] op_sel_hi:[1,0,1]
	v_sub_f32_e32 v128, v164, v166
	v_mul_f32_e32 v124, v127, v153
	v_pk_fma_f32 v[150:151], v[126:127], v[152:153], v[124:125] op_sel_hi:[1,1,0] neg_lo:[0,0,1] neg_hi:[0,0,1]
	v_mul_f32_e32 v124, v126, v153
	v_pk_fma_f32 v[126:127], v[126:127], v[152:153], v[124:125] op_sel:[1,0,0] op_sel_hi:[0,1,0]
	v_sub_f32_e32 v124, v156, v168
	v_mov_b32_e32 v131, v130
	v_mov_b32_e32 v130, v154
	v_mov_b32_e32 v127, v126
	v_mov_b32_e32 v126, v150

;     __device__ __forceinline__ void operator()(const f32x4 (&acc)[2][2][4][2], const Unit& u, int wr, int wc, int fr, int fq) const {
;     ...
;                         const int j0 = (col & 63) >> 1;
;                         const f32x4* cs = (const f32x4*)(rope + ((size_t)pos * 32 + j0) * 2);
;                         const f32x4 a = cs[0], b = cs[1];
;                         f32x4 w0, w1;
;                         w0[0] = v0[0] * a[0] - v0[1] * a[1]; w0[1] = v0[1] * a[0] + v0[0] * a[1];
;                         w0[2] = v0[2] * a[2] - v0[3] * a[3]; w0[3] = v0[3] * a[2] + v0[2] * a[3];
;                         w1[0] = v1[0] * b[0] - v1[1] * b[1]; w1[1] = v1[1] * b[0] + v1[0] * b[1];
;                         w1[2] = v1[2] * b[2] - v1[3] * b[3]; w1[3] = v1[3] * b[2] + v1[2] * b[3];
;                         v0 = w0; v1 = w1;
.LBB0_251:
	s_andn2_b64 vcc, exec, s[22:23]
	s_cbranch_vccnz .LBB0_255
	s_cmp_eq_u32 s61, 1
	s_cbranch_scc0 .LBB0_254
	v_mov_b32_e32 v148, v232
	v_mov_b32_e32 v149, v233
	v_mov_b32_e32 v150, v234
	v_mov_b32_e32 v151, v235
	v_mov_b32_e32 v152, v236
	v_mov_b32_e32 v153, v237
	v_mov_b32_e32 v154, v238
	v_mov_b32_e32 v155, v239
	v_pk_mul_f32 v[164:165], v[116:117], v[148:149] op_sel:[1,1] op_sel_hi:[0,1]
	v_pk_mul_f32 v[156:157], v[120:121], v[152:153] op_sel:[1,1] op_sel_hi:[0,1]
	v_mul_f32_e32 v0, v123, v155
	v_pk_mul_f32 v[130:131], v[120:121], v[152:153]
	v_pk_fma_f32 v[120:121], v[120:121], v[152:153], v[156:157] op_sel_hi:[1,0,1]
	v_pk_fma_f32 v[152:153], v[122:123], v[154:155], v[0:1] op_sel_hi:[1,1,0] neg_lo:[0,0,1] neg_hi:[0,0,1]
	v_mul_f32_e32 v0, v122, v155
	v_pk_fma_f32 v[122:123], v[122:123], v[154:155], v[0:1] op_sel:[1,0,0] op_sel_hi:[0,1,0]
	v_mul_f32_e32 v0, v119, v151
	v_pk_mul_f32 v[154:155], v[116:117], v[148:149]
	v_pk_fma_f32 v[116:117], v[116:117], v[148:149], v[164:165] op_sel_hi:[1,0,1]
	v_pk_fma_f32 v[148:149], v[118:119], v[150:151], v[0:1] op_sel_hi:[1,1,0] neg_lo:[0,0,1] neg_hi:[0,0,1]
	v_mul_f32_e32 v0, v118, v151
	v_pk_fma_f32 v[118:119], v[118:119], v[150:151], v[0:1] op_sel:[1,0,0] op_sel_hi:[0,1,0]
	v_sub_f32_e32 v116, v154, v164
	v_sub_f32_e32 v120, v130, v156
	v_mov_b32_e32 v123, v122
	v_mov_b32_e32 v122, v152
	v_mov_b32_e32 v119, v118
	v_mov_b32_e32 v118, v148

;     __device__ __forceinline__ void operator()(const f32x4 (&acc)[2][2][4][2], const Unit& u, int wr, int wc, int fr, int fq) const {
;     ...
;                         const int j0 = (col & 63) >> 1;
;                         const f32x4* cs = (const f32x4*)(rope + ((size_t)pos * 32 + j0) * 2);
;                         const f32x4 a = cs[0], b = cs[1];
;                         f32x4 w0, w1;
;                         w0[0] = v0[0] * a[0] - v0[1] * a[1]; w0[1] = v0[1] * a[0] + v0[0] * a[1];
;                         w0[2] = v0[2] * a[2] - v0[3] * a[3]; w0[3] = v0[3] * a[2] + v0[2] * a[3];
;                         w1[0] = v1[0] * b[0] - v1[1] * b[1]; w1[1] = v1[1] * b[0] + v1[0] * b[1];
;                         w1[2] = v1[2] * b[2] - v1[3] * b[3]; w1[3] = v1[3] * b[2] + v1[2] * b[3];
;                         v0 = w0; v1 = w1;
.LBB0_259:
	v_bitop3_b32 v0, v144, s67, 16 bitop3:0xc8
	s_andn2_b64 vcc, exec, s[0:1]
	v_lshl_add_u32 v130, v0, 6, v160
	s_cbranch_vccnz .LBB0_263
	s_cmp_eq_u32 s61, 1
	s_cbranch_scc0 .LBB0_262
	v_lshlrev_b32_e32 v117, 2, v130
	global_load_dwordx4 v[118:121], v117, s[50:51] offset:16
	global_load_dwordx4 v[148:151], v117, s[50:51]
	s_waitcnt vmcnt(1)
	v_pk_mul_f32 v[152:153], v[106:107], v[118:119] op_sel:[1,1] op_sel_hi:[0,1]
	s_waitcnt vmcnt(0)
	v_mov_b32_e32 v232, v118
	v_mov_b32_e32 v233, v119
	v_mov_b32_e32 v234, v120
	v_mov_b32_e32 v235, v121
	v_mov_b32_e32 v236, v148
	v_mov_b32_e32 v237, v149
	v_mov_b32_e32 v238, v150
	v_mov_b32_e32 v239, v151
	v_pk_mul_f32 v[128:129], v[110:111], v[148:149] op_sel:[1,1] op_sel_hi:[0,1]
	v_pk_mul_f32 v[122:123], v[110:111], v[148:149]
	v_pk_fma_f32 v[110:111], v[110:111], v[148:149], v[128:129] op_sel_hi:[1,0,1]
	s_nop 0
	v_mul_f32_e32 v110, v113, v151
	v_pk_fma_f32 v[148:149], v[112:113], v[150:151], v[110:111] op_sel_hi:[1,1,0] neg_lo:[0,0,1] neg_hi:[0,0,1]
	v_mul_f32_e32 v110, v112, v151
	v_pk_fma_f32 v[112:113], v[112:113], v[150:151], v[110:111] op_sel:[1,0,0] op_sel_hi:[0,1,0]
	v_pk_mul_f32 v[150:151], v[106:107], v[118:119]
	v_pk_fma_f32 v[106:107], v[106:107], v[118:119], v[152:153] op_sel_hi:[1,0,1]
	v_sub_f32_e32 v110, v122, v128
	v_mul_f32_e32 v106, v109, v121
	v_pk_fma_f32 v[118:119], v[108:109], v[120:121], v[106:107] op_sel_hi:[1,1,0] neg_lo:[0,0,1] neg_hi:[0,0,1]
	v_mul_f32_e32 v106, v108, v121
	v_pk_fma_f32 v[108:109], v[108:109], v[120:121], v[106:107] op_sel:[1,0,0] op_sel_hi:[0,1,0]
	v_sub_f32_e32 v106, v150, v152
	v_mov_b32_e32 v113, v112
	v_mov_b32_e32 v112, v148
	v_mov_b32_e32 v109, v108
	v_mov_b32_e32 v108, v118

;     __device__ __forceinline__ void operator()(const f32x4 (&acc)[2][2][4][2], const Unit& u, int wr, int wc, int fr, int fq) const {
;     ...
;                         const int j0 = (col & 63) >> 1;
;                         const f32x4* cs = (const f32x4*)(rope + ((size_t)pos * 32 + j0) * 2);
;                         const f32x4 a = cs[0], b = cs[1];
;                         f32x4 w0, w1;
;                         w0[0] = v0[0] * a[0] - v0[1] * a[1]; w0[1] = v0[1] * a[0] + v0[0] * a[1];
;                         w0[2] = v0[2] * a[2] - v0[3] * a[3]; w0[3] = v0[3] * a[2] + v0[2] * a[3];
;                         w1[0] = v1[0] * b[0] - v1[1] * b[1]; w1[1] = v1[1] * b[0] + v1[0] * b[1];
;                         w1[2] = v1[2] * b[2] - v1[3] * b[3]; w1[3] = v1[3] * b[2] + v1[2] * b[3];
;                         v0 = w0; v1 = w1;
.LBB0_267:
	s_andn2_b64 vcc, exec, s[0:1]
	s_cbranch_vccnz .LBB0_271
	s_cmp_eq_u32 s61, 1
	s_cbranch_scc0 .LBB0_270
	v_mov_b32_e32 v108, v232
	v_mov_b32_e32 v109, v233
	v_mov_b32_e32 v110, v234
	v_mov_b32_e32 v111, v235
	v_mov_b32_e32 v116, v236
	v_mov_b32_e32 v117, v237
	v_mov_b32_e32 v118, v238
	v_mov_b32_e32 v119, v239
	v_pk_mul_f32 v[122:123], v[98:99], v[108:109] op_sel:[1,1] op_sel_hi:[0,1]
	v_pk_mul_f32 v[120:121], v[102:103], v[116:117] op_sel:[1,1] op_sel_hi:[0,1]
	v_mul_f32_e32 v0, v105, v119
	v_pk_mul_f32 v[112:113], v[102:103], v[116:117]
	v_pk_fma_f32 v[102:103], v[102:103], v[116:117], v[120:121] op_sel_hi:[1,0,1]
	v_pk_fma_f32 v[116:117], v[104:105], v[118:119], v[0:1] op_sel_hi:[1,1,0] neg_lo:[0,0,1] neg_hi:[0,0,1]
	v_mul_f32_e32 v0, v104, v119
	v_pk_fma_f32 v[104:105], v[104:105], v[118:119], v[0:1] op_sel:[1,0,0] op_sel_hi:[0,1,0]
	v_mul_f32_e32 v0, v101, v111
	v_pk_mul_f32 v[118:119], v[98:99], v[108:109]
	v_pk_fma_f32 v[98:99], v[98:99], v[108:109], v[122:123] op_sel_hi:[1,0,1]
	v_pk_fma_f32 v[108:109], v[100:101], v[110:111], v[0:1] op_sel_hi:[1,1,0] neg_lo:[0,0,1] neg_hi:[0,0,1]
	v_mul_f32_e32 v0, v100, v111
	v_pk_fma_f32 v[100:101], v[100:101], v[110:111], v[0:1] op_sel:[1,0,0] op_sel_hi:[0,1,0]
	v_sub_f32_e32 v98, v118, v122
	v_sub_f32_e32 v102, v112, v120
	v_mov_b32_e32 v105, v104
	v_mov_b32_e32 v104, v116
	v_mov_b32_e32 v101, v100
	v_mov_b32_e32 v100, v108

;     __device__ __forceinline__ void operator()(const f32x4 (&acc)[2][2][4][2], const Unit& u, int wr, int wc, int fr, int fq) const {
;     ...
;                         const int j0 = (col & 63) >> 1;
;                         const f32x4* cs = (const f32x4*)(rope + ((size_t)pos * 32 + j0) * 2);
;                         const f32x4 a = cs[0], b = cs[1];
;                         f32x4 w0, w1;
;                         w0[0] = v0[0] * a[0] - v0[1] * a[1]; w0[1] = v0[1] * a[0] + v0[0] * a[1];
;                         w0[2] = v0[2] * a[2] - v0[3] * a[3]; w0[3] = v0[3] * a[2] + v0[2] * a[3];
;                         w1[0] = v1[0] * b[0] - v1[1] * b[1]; w1[1] = v1[1] * b[0] + v1[0] * b[1];
;                         w1[2] = v1[2] * b[2] - v1[3] * b[3]; w1[3] = v1[3] * b[2] + v1[2] * b[3];
;                         v0 = w0; v1 = w1;
.LBB0_275:
	v_bitop3_b32 v0, v144, s38, 32 bitop3:0xc8
	s_andn2_b64 vcc, exec, s[0:1]
	v_lshl_or_b32 v108, v0, 6, v160
	s_cbranch_vccnz .LBB0_279
	s_cmp_eq_u32 s61, 1
	s_cbranch_scc0 .LBB0_278
	v_lshlrev_b32_e32 v99, 2, v108
	global_load_dwordx4 v[100:103], v99, s[50:51] offset:16
	global_load_dwordx4 v[104:107], v99, s[50:51]
	s_waitcnt vmcnt(1)
	v_pk_mul_f32 v[116:117], v[90:91], v[100:101] op_sel:[1,1] op_sel_hi:[0,1]
	s_waitcnt vmcnt(0)
	v_mov_b32_e32 v232, v100
	v_mov_b32_e32 v233, v101
	v_mov_b32_e32 v234, v102
	v_mov_b32_e32 v235, v103
	v_mov_b32_e32 v236, v104
	v_mov_b32_e32 v237, v105
	v_mov_b32_e32 v238, v106
	v_mov_b32_e32 v239, v107
	v_pk_mul_f32 v[112:113], v[94:95], v[104:105] op_sel:[1,1] op_sel_hi:[0,1]
	v_pk_mul_f32 v[110:111], v[94:95], v[104:105]
	v_pk_fma_f32 v[94:95], v[94:95], v[104:105], v[112:113] op_sel_hi:[1,0,1]
	s_nop 0
	v_mul_f32_e32 v94, v97, v107
	v_pk_fma_f32 v[104:105], v[96:97], v[106:107], v[94:95] op_sel_hi:[1,1,0] neg_lo:[0,0,1] neg_hi:[0,0,1]
	v_mul_f32_e32 v94, v96, v107
	v_pk_fma_f32 v[96:97], v[96:97], v[106:107], v[94:95] op_sel:[1,0,0] op_sel_hi:[0,1,0]
	v_pk_mul_f32 v[106:107], v[90:91], v[100:101]
	v_pk_fma_f32 v[90:91], v[90:91], v[100:101], v[116:117] op_sel_hi:[1,0,1]
	v_sub_f32_e32 v94, v110, v112
	v_mul_f32_e32 v90, v93, v103
	v_pk_fma_f32 v[100:101], v[92:93], v[102:103], v[90:91] op_sel_hi:[1,1,0] neg_lo:[0,0,1] neg_hi:[0,0,1]
	v_mul_f32_e32 v90, v92, v103
	v_pk_fma_f32 v[92:93], v[92:93], v[102:103], v[90:91] op_sel:[1,0,0] op_sel_hi:[0,1,0]
	v_sub_f32_e32 v90, v106, v116
	v_mov_b32_e32 v97, v96
	v_mov_b32_e32 v96, v104
	v_mov_b32_e32 v93, v92
	v_mov_b32_e32 v92, v100

;     __device__ __forceinline__ void operator()(const f32x4 (&acc)[2][2][4][2], const Unit& u, int wr, int wc, int fr, int fq) const {
;     ...
;                         const int j0 = (col & 63) >> 1;
;                         const f32x4* cs = (const f32x4*)(rope + ((size_t)pos * 32 + j0) * 2);
;                         const f32x4 a = cs[0], b = cs[1];
;                         f32x4 w0, w1;
;                         w0[0] = v0[0] * a[0] - v0[1] * a[1]; w0[1] = v0[1] * a[0] + v0[0] * a[1];
;                         w0[2] = v0[2] * a[2] - v0[3] * a[3]; w0[3] = v0[3] * a[2] + v0[2] * a[3];
;                         w1[0] = v1[0] * b[0] - v1[1] * b[1]; w1[1] = v1[1] * b[0] + v1[0] * b[1];
;                         w1[2] = v1[2] * b[2] - v1[3] * b[3]; w1[3] = v1[3] * b[2] + v1[2] * b[3];
;                         v0 = w0; v1 = w1;
.LBB0_283:
	s_andn2_b64 vcc, exec, s[0:1]
	s_cbranch_vccnz .LBB0_287
	s_cmp_eq_u32 s61, 1
	s_cbranch_scc0 .LBB0_286
	v_mov_b32_e32 v92, v232
	v_mov_b32_e32 v93, v233
	v_mov_b32_e32 v94, v234
	v_mov_b32_e32 v95, v235
	v_mov_b32_e32 v96, v236
	v_mov_b32_e32 v97, v237
	v_mov_b32_e32 v98, v238
	v_mov_b32_e32 v99, v239
	v_pk_mul_f32 v[104:105], v[82:83], v[92:93] op_sel:[1,1] op_sel_hi:[0,1]
	v_pk_mul_f32 v[102:103], v[86:87], v[96:97] op_sel:[1,1] op_sel_hi:[0,1]
	v_mul_f32_e32 v0, v89, v99
	v_pk_mul_f32 v[100:101], v[86:87], v[96:97]
	v_pk_fma_f32 v[86:87], v[86:87], v[96:97], v[102:103] op_sel_hi:[1,0,1]
	v_pk_fma_f32 v[96:97], v[88:89], v[98:99], v[0:1] op_sel_hi:[1,1,0] neg_lo:[0,0,1] neg_hi:[0,0,1]
	v_mul_f32_e32 v0, v88, v99
	v_pk_fma_f32 v[88:89], v[88:89], v[98:99], v[0:1] op_sel:[1,0,0] op_sel_hi:[0,1,0]
	v_mul_f32_e32 v0, v85, v95
	v_pk_mul_f32 v[98:99], v[82:83], v[92:93]
	v_pk_fma_f32 v[82:83], v[82:83], v[92:93], v[104:105] op_sel_hi:[1,0,1]
	v_pk_fma_f32 v[92:93], v[84:85], v[94:95], v[0:1] op_sel_hi:[1,1,0] neg_lo:[0,0,1] neg_hi:[0,0,1]
	v_mul_f32_e32 v0, v84, v95
	v_pk_fma_f32 v[84:85], v[84:85], v[94:95], v[0:1] op_sel:[1,0,0] op_sel_hi:[0,1,0]
	v_sub_f32_e32 v82, v98, v104
	v_sub_f32_e32 v86, v100, v102
	v_mov_b32_e32 v89, v88
	v_mov_b32_e32 v88, v96
	v_mov_b32_e32 v85, v84
	v_mov_b32_e32 v84, v92

;     __device__ __forceinline__ void operator()(const f32x4 (&acc)[2][2][4][2], const Unit& u, int wr, int wc, int fr, int fq) const {
;     ...
;                         const int j0 = (col & 63) >> 1;
;                         const f32x4* cs = (const f32x4*)(rope + ((size_t)pos * 32 + j0) * 2);
;                         const f32x4 a = cs[0], b = cs[1];
;                         f32x4 w0, w1;
;                         w0[0] = v0[0] * a[0] - v0[1] * a[1]; w0[1] = v0[1] * a[0] + v0[0] * a[1];
;                         w0[2] = v0[2] * a[2] - v0[3] * a[3]; w0[3] = v0[3] * a[2] + v0[2] * a[3];
;                         w1[0] = v1[0] * b[0] - v1[1] * b[1]; w1[1] = v1[1] * b[0] + v1[0] * b[1];
;                         w1[2] = v1[2] * b[2] - v1[3] * b[3]; w1[3] = v1[3] * b[2] + v1[2] * b[3];
;                         v0 = w0; v1 = w1;
.LBB0_291:
	v_bitop3_b32 v0, v144, s39, 48 bitop3:0xc8
	s_andn2_b64 vcc, exec, s[0:1]
	v_lshl_add_u32 v92, v0, 6, v160
	s_cbranch_vccnz .LBB0_295
	s_cmp_eq_u32 s61, 1
	s_cbranch_scc0 .LBB0_294
	v_lshlrev_b32_e32 v83, 2, v92
	global_load_dwordx4 v[84:87], v83, s[50:51] offset:16
	global_load_dwordx4 v[88:91], v83, s[50:51]
	s_waitcnt vmcnt(1)
	v_pk_mul_f32 v[98:99], v[74:75], v[84:85] op_sel:[1,1] op_sel_hi:[0,1]
	s_waitcnt vmcnt(0)
	v_mov_b32_e32 v232, v84
	v_mov_b32_e32 v233, v85
	v_mov_b32_e32 v234, v86
	v_mov_b32_e32 v235, v87
	v_mov_b32_e32 v236, v88
	v_mov_b32_e32 v237, v89
	v_mov_b32_e32 v238, v90
	v_mov_b32_e32 v239, v91
	v_pk_mul_f32 v[96:97], v[78:79], v[88:89] op_sel:[1,1] op_sel_hi:[0,1]
	v_pk_mul_f32 v[94:95], v[78:79], v[88:89]
	v_pk_fma_f32 v[78:79], v[78:79], v[88:89], v[96:97] op_sel_hi:[1,0,1]
	s_nop 0
	v_mul_f32_e32 v78, v81, v91
	v_pk_fma_f32 v[88:89], v[80:81], v[90:91], v[78:79] op_sel_hi:[1,1,0] neg_lo:[0,0,1] neg_hi:[0,0,1]
	v_mul_f32_e32 v78, v80, v91
	v_pk_fma_f32 v[80:81], v[80:81], v[90:91], v[78:79] op_sel:[1,0,0] op_sel_hi:[0,1,0]
	v_pk_mul_f32 v[90:91], v[74:75], v[84:85]
	v_pk_fma_f32 v[74:75], v[74:75], v[84:85], v[98:99] op_sel_hi:[1,0,1]
	v_sub_f32_e32 v78, v94, v96
	v_mul_f32_e32 v74, v77, v87
	v_pk_fma_f32 v[84:85], v[76:77], v[86:87], v[74:75] op_sel_hi:[1,1,0] neg_lo:[0,0,1] neg_hi:[0,0,1]
	v_mul_f32_e32 v74, v76, v87
	v_pk_fma_f32 v[76:77], v[76:77], v[86:87], v[74:75] op_sel:[1,0,0] op_sel_hi:[0,1,0]
	v_sub_f32_e32 v74, v90, v98
	v_mov_b32_e32 v81, v80
	v_mov_b32_e32 v80, v88
	v_mov_b32_e32 v77, v76
	v_mov_b32_e32 v76, v84

;     __device__ __forceinline__ void operator()(const f32x4 (&acc)[2][2][4][2], const Unit& u, int wr, int wc, int fr, int fq) const {
;     ...
;                         const int j0 = (col & 63) >> 1;
;                         const f32x4* cs = (const f32x4*)(rope + ((size_t)pos * 32 + j0) * 2);
;                         const f32x4 a = cs[0], b = cs[1];
;                         f32x4 w0, w1;
;                         w0[0] = v0[0] * a[0] - v0[1] * a[1]; w0[1] = v0[1] * a[0] + v0[0] * a[1];
;                         w0[2] = v0[2] * a[2] - v0[3] * a[3]; w0[3] = v0[3] * a[2] + v0[2] * a[3];
;                         w1[0] = v1[0] * b[0] - v1[1] * b[1]; w1[1] = v1[1] * b[0] + v1[0] * b[1];
;                         w1[2] = v1[2] * b[2] - v1[3] * b[3]; w1[3] = v1[3] * b[2] + v1[2] * b[3];
;                         v0 = w0; v1 = w1;
.LBB0_299:
	s_andn2_b64 vcc, exec, s[0:1]
	s_cbranch_vccnz .LBB0_303
	s_cmp_eq_u32 s61, 1
	s_cbranch_scc0 .LBB0_302
	v_mov_b32_e32 v76, v232
	v_mov_b32_e32 v77, v233
	v_mov_b32_e32 v78, v234
	v_mov_b32_e32 v79, v235
	v_mov_b32_e32 v80, v236
	v_mov_b32_e32 v81, v237
	v_mov_b32_e32 v82, v238
	v_mov_b32_e32 v83, v239
	v_pk_mul_f32 v[88:89], v[66:67], v[76:77] op_sel:[1,1] op_sel_hi:[0,1]
	v_pk_mul_f32 v[86:87], v[70:71], v[80:81] op_sel:[1,1] op_sel_hi:[0,1]
	v_mul_f32_e32 v0, v73, v83
	v_pk_mul_f32 v[84:85], v[70:71], v[80:81]
	v_pk_fma_f32 v[70:71], v[70:71], v[80:81], v[86:87] op_sel_hi:[1,0,1]
	v_pk_fma_f32 v[80:81], v[72:73], v[82:83], v[0:1] op_sel_hi:[1,1,0] neg_lo:[0,0,1] neg_hi:[0,0,1]
	v_mul_f32_e32 v0, v72, v83
	v_pk_fma_f32 v[72:73], v[72:73], v[82:83], v[0:1] op_sel:[1,0,0] op_sel_hi:[0,1,0]
	v_mul_f32_e32 v0, v69, v79
	v_pk_mul_f32 v[82:83], v[66:67], v[76:77]
	v_pk_fma_f32 v[66:67], v[66:67], v[76:77], v[88:89] op_sel_hi:[1,0,1]
	v_pk_fma_f32 v[76:77], v[68:69], v[78:79], v[0:1] op_sel_hi:[1,1,0] neg_lo:[0,0,1] neg_hi:[0,0,1]
	v_mul_f32_e32 v0, v68, v79
	v_pk_fma_f32 v[68:69], v[68:69], v[78:79], v[0:1] op_sel:[1,0,0] op_sel_hi:[0,1,0]
	v_sub_f32_e32 v66, v82, v88
	v_sub_f32_e32 v70, v84, v86
	v_mov_b32_e32 v73, v72
	v_mov_b32_e32 v72, v80
	v_mov_b32_e32 v69, v68
	v_mov_b32_e32 v68, v76

;     __device__ __forceinline__ void operator()(const f32x4 (&acc)[2][2][4][2], const Unit& u, int wr, int wc, int fr, int fq) const {
;     ...
;                         const int j0 = (col & 63) >> 1;
;                         const f32x4* cs = (const f32x4*)(rope + ((size_t)pos * 32 + j0) * 2);
;                         const f32x4 a = cs[0], b = cs[1];
;                         f32x4 w0, w1;
;                         w0[0] = v0[0] * a[0] - v0[1] * a[1]; w0[1] = v0[1] * a[0] + v0[0] * a[1];
;                         w0[2] = v0[2] * a[2] - v0[3] * a[3]; w0[3] = v0[3] * a[2] + v0[2] * a[3];
;                         w1[0] = v1[0] * b[0] - v1[1] * b[1]; w1[1] = v1[1] * b[0] + v1[0] * b[1];
;                         w1[2] = v1[2] * b[2] - v1[3] * b[3]; w1[3] = v1[3] * b[2] + v1[2] * b[3];
;                         v0 = w0; v1 = w1;
.LBB0_307:
	v_bitop3_b32 v0, s63, v220, v115 bitop3:0xc8
	s_andn2_b64 vcc, exec, s[0:1]
	v_lshl_or_b32 v67, v0, 6, v160
	s_cbranch_vccnz .LBB0_311
	s_cmp_eq_u32 s61, 1
	s_cbranch_scc0 .LBB0_310
	v_lshlrev_b32_e32 v71, 2, v67
	global_load_dwordx4 v[72:75], v71, s[50:51] offset:16
	global_load_dwordx4 v[76:79], v71, s[50:51]
	s_waitcnt vmcnt(1)
	v_pk_mul_f32 v[84:85], v[58:59], v[72:73] op_sel:[1,1] op_sel_hi:[0,1]
	s_waitcnt vmcnt(0)
	v_mov_b32_e32 v232, v72
	v_mov_b32_e32 v233, v73
	v_mov_b32_e32 v234, v74
	v_mov_b32_e32 v235, v75
	v_mov_b32_e32 v236, v76
	v_mov_b32_e32 v237, v77
	v_mov_b32_e32 v238, v78
	v_mov_b32_e32 v239, v79
	v_pk_mul_f32 v[82:83], v[62:63], v[76:77] op_sel:[1,1] op_sel_hi:[0,1]
	v_pk_mul_f32 v[80:81], v[62:63], v[76:77]
	v_pk_fma_f32 v[62:63], v[62:63], v[76:77], v[82:83] op_sel_hi:[1,0,1]
	s_nop 0
	v_mul_f32_e32 v62, v65, v79
	v_pk_fma_f32 v[76:77], v[64:65], v[78:79], v[62:63] op_sel_hi:[1,1,0] neg_lo:[0,0,1] neg_hi:[0,0,1]
	v_mul_f32_e32 v62, v64, v79
	v_pk_fma_f32 v[64:65], v[64:65], v[78:79], v[62:63] op_sel:[1,0,0] op_sel_hi:[0,1,0]
	v_pk_mul_f32 v[78:79], v[58:59], v[72:73]
	v_pk_fma_f32 v[58:59], v[58:59], v[72:73], v[84:85] op_sel_hi:[1,0,1]
	v_sub_f32_e32 v62, v80, v82
	v_mul_f32_e32 v58, v61, v75
	v_pk_fma_f32 v[72:73], v[60:61], v[74:75], v[58:59] op_sel_hi:[1,1,0] neg_lo:[0,0,1] neg_hi:[0,0,1]
	v_mul_f32_e32 v58, v60, v75
	v_pk_fma_f32 v[60:61], v[60:61], v[74:75], v[58:59] op_sel:[1,0,0] op_sel_hi:[0,1,0]
	v_sub_f32_e32 v58, v78, v84
	v_mov_b32_e32 v65, v64
	v_mov_b32_e32 v64, v76
	v_mov_b32_e32 v61, v60
	v_mov_b32_e32 v60, v72

;     __device__ __forceinline__ void operator()(const f32x4 (&acc)[2][2][4][2], const Unit& u, int wr, int wc, int fr, int fq) const {
;     ...
;                         const int j0 = (col & 63) >> 1;
;                         const f32x4* cs = (const f32x4*)(rope + ((size_t)pos * 32 + j0) * 2);
;                         const f32x4 a = cs[0], b = cs[1];
;                         f32x4 w0, w1;
;                         w0[0] = v0[0] * a[0] - v0[1] * a[1]; w0[1] = v0[1] * a[0] + v0[0] * a[1];
;                         w0[2] = v0[2] * a[2] - v0[3] * a[3]; w0[3] = v0[3] * a[2] + v0[2] * a[3];
;                         w1[0] = v1[0] * b[0] - v1[1] * b[1]; w1[1] = v1[1] * b[0] + v1[0] * b[1];
;                         w1[2] = v1[2] * b[2] - v1[3] * b[3]; w1[3] = v1[3] * b[2] + v1[2] * b[3];
;                         v0 = w0; v1 = w1;
.LBB0_315:
	s_andn2_b64 vcc, exec, s[0:1]
	s_cbranch_vccnz .LBB0_319
	s_cmp_eq_u32 s61, 1
	s_cbranch_scc0 .LBB0_318
	v_mov_b32_e32 v60, v232
	v_mov_b32_e32 v61, v233
	v_mov_b32_e32 v62, v234
	v_mov_b32_e32 v63, v235
	v_mov_b32_e32 v70, v236
	v_mov_b32_e32 v71, v237
	v_mov_b32_e32 v72, v238
	v_mov_b32_e32 v73, v239
	v_pk_mul_f32 v[76:77], v[50:51], v[60:61] op_sel:[1,1] op_sel_hi:[0,1]
	v_pk_mul_f32 v[74:75], v[54:55], v[70:71] op_sel:[1,1] op_sel_hi:[0,1]
	v_mul_f32_e32 v0, v57, v73
	v_pk_mul_f32 v[64:65], v[54:55], v[70:71]
	v_pk_fma_f32 v[54:55], v[54:55], v[70:71], v[74:75] op_sel_hi:[1,0,1]
	v_pk_fma_f32 v[70:71], v[56:57], v[72:73], v[0:1] op_sel_hi:[1,1,0] neg_lo:[0,0,1] neg_hi:[0,0,1]
	v_mul_f32_e32 v0, v56, v73
	v_pk_fma_f32 v[56:57], v[56:57], v[72:73], v[0:1] op_sel:[1,0,0] op_sel_hi:[0,1,0]
	v_mul_f32_e32 v0, v53, v63
	v_pk_mul_f32 v[72:73], v[50:51], v[60:61]
	v_pk_fma_f32 v[50:51], v[50:51], v[60:61], v[76:77] op_sel_hi:[1,0,1]
	v_pk_fma_f32 v[60:61], v[52:53], v[62:63], v[0:1] op_sel_hi:[1,1,0] neg_lo:[0,0,1] neg_hi:[0,0,1]
	v_mul_f32_e32 v0, v52, v63
	v_pk_fma_f32 v[52:53], v[52:53], v[62:63], v[0:1] op_sel:[1,0,0] op_sel_hi:[0,1,0]
	v_sub_f32_e32 v50, v72, v76
	v_sub_f32_e32 v54, v64, v74
	v_mov_b32_e32 v57, v56
	v_mov_b32_e32 v56, v70
	v_mov_b32_e32 v53, v52
	v_mov_b32_e32 v52, v60

;     __device__ __forceinline__ void operator()(const f32x4 (&acc)[2][2][4][2], const Unit& u, int wr, int wc, int fr, int fq) const {
;     ...
;                         const int j0 = (col & 63) >> 1;
;                         const f32x4* cs = (const f32x4*)(rope + ((size_t)pos * 32 + j0) * 2);
;                         const f32x4 a = cs[0], b = cs[1];
;                         f32x4 w0, w1;
;                         w0[0] = v0[0] * a[0] - v0[1] * a[1]; w0[1] = v0[1] * a[0] + v0[0] * a[1];
;                         w0[2] = v0[2] * a[2] - v0[3] * a[3]; w0[3] = v0[3] * a[2] + v0[2] * a[3];
;                         w1[0] = v1[0] * b[0] - v1[1] * b[1]; w1[1] = v1[1] * b[0] + v1[0] * b[1];
;                         w1[2] = v1[2] * b[2] - v1[3] * b[3]; w1[3] = v1[3] * b[2] + v1[2] * b[3];
;                         v0 = w0; v1 = w1;
.LBB0_323:
	v_bitop3_b32 v0, v66, s67, 16 bitop3:0xc8
	s_andn2_b64 vcc, exec, s[0:1]
	v_lshl_add_u32 v60, v0, 6, v160
	s_cbranch_vccnz .LBB0_327
	s_cmp_eq_u32 s61, 1
	s_cbranch_scc0 .LBB0_326
	v_lshlrev_b32_e32 v51, 2, v60
	global_load_dwordx4 v[52:55], v51, s[50:51] offset:16
	global_load_dwordx4 v[56:59], v51, s[50:51]
	s_waitcnt vmcnt(1)
	v_pk_mul_f32 v[70:71], v[42:43], v[52:53] op_sel:[1,1] op_sel_hi:[0,1]
	s_waitcnt vmcnt(0)
	v_mov_b32_e32 v232, v52
	v_mov_b32_e32 v233, v53
	v_mov_b32_e32 v234, v54
	v_mov_b32_e32 v235, v55
	v_mov_b32_e32 v236, v56
	v_mov_b32_e32 v237, v57
	v_mov_b32_e32 v238, v58
	v_mov_b32_e32 v239, v59
	v_pk_mul_f32 v[64:65], v[46:47], v[56:57] op_sel:[1,1] op_sel_hi:[0,1]
	v_pk_mul_f32 v[62:63], v[46:47], v[56:57]
	v_pk_fma_f32 v[46:47], v[46:47], v[56:57], v[64:65] op_sel_hi:[1,0,1]
	s_nop 0
	v_mul_f32_e32 v46, v49, v59
	v_pk_fma_f32 v[56:57], v[48:49], v[58:59], v[46:47] op_sel_hi:[1,1,0] neg_lo:[0,0,1] neg_hi:[0,0,1]
	v_mul_f32_e32 v46, v48, v59
	v_pk_fma_f32 v[48:49], v[48:49], v[58:59], v[46:47] op_sel:[1,0,0] op_sel_hi:[0,1,0]
	v_pk_mul_f32 v[58:59], v[42:43], v[52:53]
	v_pk_fma_f32 v[42:43], v[42:43], v[52:53], v[70:71] op_sel_hi:[1,0,1]
	v_sub_f32_e32 v46, v62, v64
	v_mul_f32_e32 v42, v45, v55
	v_pk_fma_f32 v[52:53], v[44:45], v[54:55], v[42:43] op_sel_hi:[1,1,0] neg_lo:[0,0,1] neg_hi:[0,0,1]
	v_mul_f32_e32 v42, v44, v55
	v_pk_fma_f32 v[44:45], v[44:45], v[54:55], v[42:43] op_sel:[1,0,0] op_sel_hi:[0,1,0]
	v_sub_f32_e32 v42, v58, v70
	v_mov_b32_e32 v49, v48
	v_mov_b32_e32 v48, v56
	v_mov_b32_e32 v45, v44
	v_mov_b32_e32 v44, v52

;     __device__ __forceinline__ void operator()(const f32x4 (&acc)[2][2][4][2], const Unit& u, int wr, int wc, int fr, int fq) const {
;     ...
;                         const int j0 = (col & 63) >> 1;
;                         const f32x4* cs = (const f32x4*)(rope + ((size_t)pos * 32 + j0) * 2);
;                         const f32x4 a = cs[0], b = cs[1];
;                         f32x4 w0, w1;
;                         w0[0] = v0[0] * a[0] - v0[1] * a[1]; w0[1] = v0[1] * a[0] + v0[0] * a[1];
;                         w0[2] = v0[2] * a[2] - v0[3] * a[3]; w0[3] = v0[3] * a[2] + v0[2] * a[3];
;                         w1[0] = v1[0] * b[0] - v1[1] * b[1]; w1[1] = v1[1] * b[0] + v1[0] * b[1];
;                         w1[2] = v1[2] * b[2] - v1[3] * b[3]; w1[3] = v1[3] * b[2] + v1[2] * b[3];
;                         v0 = w0; v1 = w1;
.LBB0_331:
	s_andn2_b64 vcc, exec, s[0:1]
	s_cbranch_vccnz .LBB0_335
	s_cmp_eq_u32 s61, 1
	s_cbranch_scc0 .LBB0_334
	v_mov_b32_e32 v44, v232
	v_mov_b32_e32 v45, v233
	v_mov_b32_e32 v46, v234
	v_mov_b32_e32 v47, v235
	v_mov_b32_e32 v48, v236
	v_mov_b32_e32 v49, v237
	v_mov_b32_e32 v50, v238
	v_mov_b32_e32 v51, v239
	v_pk_mul_f32 v[56:57], v[34:35], v[44:45] op_sel:[1,1] op_sel_hi:[0,1]
	v_pk_mul_f32 v[54:55], v[38:39], v[48:49] op_sel:[1,1] op_sel_hi:[0,1]
	v_mul_f32_e32 v0, v41, v51
	v_pk_mul_f32 v[52:53], v[38:39], v[48:49]
	v_pk_fma_f32 v[38:39], v[38:39], v[48:49], v[54:55] op_sel_hi:[1,0,1]
	v_pk_fma_f32 v[48:49], v[40:41], v[50:51], v[0:1] op_sel_hi:[1,1,0] neg_lo:[0,0,1] neg_hi:[0,0,1]
	v_mul_f32_e32 v0, v40, v51
	v_pk_fma_f32 v[40:41], v[40:41], v[50:51], v[0:1] op_sel:[1,0,0] op_sel_hi:[0,1,0]
	v_mul_f32_e32 v0, v37, v47
	v_pk_mul_f32 v[50:51], v[34:35], v[44:45]
	v_pk_fma_f32 v[34:35], v[34:35], v[44:45], v[56:57] op_sel_hi:[1,0,1]
	v_pk_fma_f32 v[44:45], v[36:37], v[46:47], v[0:1] op_sel_hi:[1,1,0] neg_lo:[0,0,1] neg_hi:[0,0,1]
	v_mul_f32_e32 v0, v36, v47
	v_pk_fma_f32 v[36:37], v[36:37], v[46:47], v[0:1] op_sel:[1,0,0] op_sel_hi:[0,1,0]
	v_sub_f32_e32 v34, v50, v56
	v_sub_f32_e32 v38, v52, v54
	v_mov_b32_e32 v41, v40
	v_mov_b32_e32 v40, v48
	v_mov_b32_e32 v37, v36
	v_mov_b32_e32 v36, v44

;     __device__ __forceinline__ void operator()(const f32x4 (&acc)[2][2][4][2], const Unit& u, int wr, int wc, int fr, int fq) const {
;     ...
;                         const int j0 = (col & 63) >> 1;
;                         const f32x4* cs = (const f32x4*)(rope + ((size_t)pos * 32 + j0) * 2);
;                         const f32x4 a = cs[0], b = cs[1];
;                         f32x4 w0, w1;
;                         w0[0] = v0[0] * a[0] - v0[1] * a[1]; w0[1] = v0[1] * a[0] + v0[0] * a[1];
;                         w0[2] = v0[2] * a[2] - v0[3] * a[3]; w0[3] = v0[3] * a[2] + v0[2] * a[3];
;                         w1[0] = v1[0] * b[0] - v1[1] * b[1]; w1[1] = v1[1] * b[0] + v1[0] * b[1];
;                         w1[2] = v1[2] * b[2] - v1[3] * b[3]; w1[3] = v1[3] * b[2] + v1[2] * b[3];
;                         v0 = w0; v1 = w1;
.LBB0_339:
	v_bitop3_b32 v0, v66, s38, 32 bitop3:0xc8
	s_andn2_b64 vcc, exec, s[0:1]
	v_lshl_or_b32 v44, v0, 6, v160
	s_cbranch_vccnz .LBB0_343
	s_cmp_eq_u32 s61, 1
	s_cbranch_scc0 .LBB0_342
	v_lshlrev_b32_e32 v35, 2, v44
	global_load_dwordx4 v[36:39], v35, s[50:51] offset:16
	global_load_dwordx4 v[40:43], v35, s[50:51]
	s_waitcnt vmcnt(1)
	v_pk_mul_f32 v[50:51], v[26:27], v[36:37] op_sel:[1,1] op_sel_hi:[0,1]
	s_waitcnt vmcnt(0)
	v_mov_b32_e32 v232, v36
	v_mov_b32_e32 v233, v37
	v_mov_b32_e32 v234, v38
	v_mov_b32_e32 v235, v39
	v_mov_b32_e32 v236, v40
	v_mov_b32_e32 v237, v41
	v_mov_b32_e32 v238, v42
	v_mov_b32_e32 v239, v43
	v_pk_mul_f32 v[48:49], v[30:31], v[40:41] op_sel:[1,1] op_sel_hi:[0,1]
	v_pk_mul_f32 v[46:47], v[30:31], v[40:41]
	v_pk_fma_f32 v[30:31], v[30:31], v[40:41], v[48:49] op_sel_hi:[1,0,1]
	s_nop 0
	v_mul_f32_e32 v30, v33, v43
	v_pk_fma_f32 v[40:41], v[32:33], v[42:43], v[30:31] op_sel_hi:[1,1,0] neg_lo:[0,0,1] neg_hi:[0,0,1]
	v_mul_f32_e32 v30, v32, v43
	v_pk_fma_f32 v[32:33], v[32:33], v[42:43], v[30:31] op_sel:[1,0,0] op_sel_hi:[0,1,0]
	v_pk_mul_f32 v[42:43], v[26:27], v[36:37]
	v_pk_fma_f32 v[26:27], v[26:27], v[36:37], v[50:51] op_sel_hi:[1,0,1]
	v_sub_f32_e32 v30, v46, v48
	v_mul_f32_e32 v26, v29, v39
	v_pk_fma_f32 v[36:37], v[28:29], v[38:39], v[26:27] op_sel_hi:[1,1,0] neg_lo:[0,0,1] neg_hi:[0,0,1]
	v_mul_f32_e32 v26, v28, v39
	v_pk_fma_f32 v[28:29], v[28:29], v[38:39], v[26:27] op_sel:[1,0,0] op_sel_hi:[0,1,0]
	v_sub_f32_e32 v26, v42, v50
	v_mov_b32_e32 v33, v32
	v_mov_b32_e32 v32, v40
	v_mov_b32_e32 v29, v28
	v_mov_b32_e32 v28, v36

;     __device__ __forceinline__ void operator()(const f32x4 (&acc)[2][2][4][2], const Unit& u, int wr, int wc, int fr, int fq) const {
;     ...
;                         const int j0 = (col & 63) >> 1;
;                         const f32x4* cs = (const f32x4*)(rope + ((size_t)pos * 32 + j0) * 2);
;                         const f32x4 a = cs[0], b = cs[1];
;                         f32x4 w0, w1;
;                         w0[0] = v0[0] * a[0] - v0[1] * a[1]; w0[1] = v0[1] * a[0] + v0[0] * a[1];
;                         w0[2] = v0[2] * a[2] - v0[3] * a[3]; w0[3] = v0[3] * a[2] + v0[2] * a[3];
;                         w1[0] = v1[0] * b[0] - v1[1] * b[1]; w1[1] = v1[1] * b[0] + v1[0] * b[1];
;                         w1[2] = v1[2] * b[2] - v1[3] * b[3]; w1[3] = v1[3] * b[2] + v1[2] * b[3];
;                         v0 = w0; v1 = w1;
.LBB0_347:
	s_andn2_b64 vcc, exec, s[0:1]
	s_cbranch_vccnz .LBB0_351
	s_cmp_eq_u32 s61, 1
	s_cbranch_scc0 .LBB0_350
	v_mov_b32_e32 v28, v232
	v_mov_b32_e32 v29, v233
	v_mov_b32_e32 v30, v234
	v_mov_b32_e32 v31, v235
	v_mov_b32_e32 v32, v236
	v_mov_b32_e32 v33, v237
	v_mov_b32_e32 v34, v238
	v_mov_b32_e32 v35, v239
	v_pk_mul_f32 v[40:41], v[18:19], v[28:29] op_sel:[1,1] op_sel_hi:[0,1]
	v_pk_mul_f32 v[38:39], v[22:23], v[32:33] op_sel:[1,1] op_sel_hi:[0,1]
	v_mul_f32_e32 v0, v25, v35
	v_pk_mul_f32 v[36:37], v[22:23], v[32:33]
	v_pk_fma_f32 v[22:23], v[22:23], v[32:33], v[38:39] op_sel_hi:[1,0,1]
	v_pk_fma_f32 v[32:33], v[24:25], v[34:35], v[0:1] op_sel_hi:[1,1,0] neg_lo:[0,0,1] neg_hi:[0,0,1]
	v_mul_f32_e32 v0, v24, v35
	v_pk_fma_f32 v[24:25], v[24:25], v[34:35], v[0:1] op_sel:[1,0,0] op_sel_hi:[0,1,0]
	v_mul_f32_e32 v0, v21, v31
	v_pk_mul_f32 v[34:35], v[18:19], v[28:29]
	v_pk_fma_f32 v[18:19], v[18:19], v[28:29], v[40:41] op_sel_hi:[1,0,1]
	v_pk_fma_f32 v[28:29], v[20:21], v[30:31], v[0:1] op_sel_hi:[1,1,0] neg_lo:[0,0,1] neg_hi:[0,0,1]
	v_mul_f32_e32 v0, v20, v31
	v_pk_fma_f32 v[20:21], v[20:21], v[30:31], v[0:1] op_sel:[1,0,0] op_sel_hi:[0,1,0]
	v_sub_f32_e32 v18, v34, v40
	v_sub_f32_e32 v22, v36, v38
	v_mov_b32_e32 v25, v24
	v_mov_b32_e32 v24, v32
	v_mov_b32_e32 v21, v20
	v_mov_b32_e32 v20, v28

;     __device__ __forceinline__ void operator()(const f32x4 (&acc)[2][2][4][2], const Unit& u, int wr, int wc, int fr, int fq) const {
;     ...
;                         const int j0 = (col & 63) >> 1;
;                         const f32x4* cs = (const f32x4*)(rope + ((size_t)pos * 32 + j0) * 2);
;                         const f32x4 a = cs[0], b = cs[1];
;                         f32x4 w0, w1;
;                         w0[0] = v0[0] * a[0] - v0[1] * a[1]; w0[1] = v0[1] * a[0] + v0[0] * a[1];
;                         w0[2] = v0[2] * a[2] - v0[3] * a[3]; w0[3] = v0[3] * a[2] + v0[2] * a[3];
;                         w1[0] = v1[0] * b[0] - v1[1] * b[1]; w1[1] = v1[1] * b[0] + v1[0] * b[1];
;                         w1[2] = v1[2] * b[2] - v1[3] * b[3]; w1[3] = v1[3] * b[2] + v1[2] * b[3];
;                         v0 = w0; v1 = w1;
.LBB0_355:
	v_bitop3_b32 v0, v66, s39, 48 bitop3:0xc8
	s_andn2_b64 vcc, exec, s[0:1]
	v_lshl_add_u32 v28, v0, 6, v160
	s_cbranch_vccnz .LBB0_359
	s_cmp_eq_u32 s61, 1
	s_cbranch_scc0 .LBB0_358
	v_lshlrev_b32_e32 v19, 2, v28
	global_load_dwordx4 v[20:23], v19, s[50:51] offset:16
	global_load_dwordx4 v[24:27], v19, s[50:51]
	s_waitcnt vmcnt(1)
	v_pk_mul_f32 v[34:35], v[10:11], v[20:21] op_sel:[1,1] op_sel_hi:[0,1]
	s_waitcnt vmcnt(0)
	v_mov_b32_e32 v232, v20
	v_mov_b32_e32 v233, v21
	v_mov_b32_e32 v234, v22
	v_mov_b32_e32 v235, v23
	v_mov_b32_e32 v236, v24
	v_mov_b32_e32 v237, v25
	v_mov_b32_e32 v238, v26
	v_mov_b32_e32 v239, v27
	v_pk_mul_f32 v[32:33], v[14:15], v[24:25] op_sel:[1,1] op_sel_hi:[0,1]
	v_pk_mul_f32 v[30:31], v[14:15], v[24:25]
	v_pk_fma_f32 v[14:15], v[14:15], v[24:25], v[32:33] op_sel_hi:[1,0,1]
	s_nop 0
	v_mul_f32_e32 v14, v17, v27
	v_pk_fma_f32 v[24:25], v[16:17], v[26:27], v[14:15] op_sel_hi:[1,1,0] neg_lo:[0,0,1] neg_hi:[0,0,1]
	v_mul_f32_e32 v14, v16, v27
	v_pk_fma_f32 v[16:17], v[16:17], v[26:27], v[14:15] op_sel:[1,0,0] op_sel_hi:[0,1,0]
	v_pk_mul_f32 v[26:27], v[10:11], v[20:21]
	v_pk_fma_f32 v[10:11], v[10:11], v[20:21], v[34:35] op_sel_hi:[1,0,1]
	v_sub_f32_e32 v14, v30, v32
	v_mul_f32_e32 v10, v13, v23
	v_pk_fma_f32 v[20:21], v[12:13], v[22:23], v[10:11] op_sel_hi:[1,1,0] neg_lo:[0,0,1] neg_hi:[0,0,1]
	v_mul_f32_e32 v10, v12, v23
	v_pk_fma_f32 v[12:13], v[12:13], v[22:23], v[10:11] op_sel:[1,0,0] op_sel_hi:[0,1,0]
	v_sub_f32_e32 v10, v26, v34
	v_mov_b32_e32 v17, v16
	v_mov_b32_e32 v16, v24
	v_mov_b32_e32 v13, v12
	v_mov_b32_e32 v12, v20

;     __device__ __forceinline__ void operator()(const f32x4 (&acc)[2][2][4][2], const Unit& u, int wr, int wc, int fr, int fq) const {
;     ...
;                         const int j0 = (col & 63) >> 1;
;                         const f32x4* cs = (const f32x4*)(rope + ((size_t)pos * 32 + j0) * 2);
;                         const f32x4 a = cs[0], b = cs[1];
;                         f32x4 w0, w1;
;                         w0[0] = v0[0] * a[0] - v0[1] * a[1]; w0[1] = v0[1] * a[0] + v0[0] * a[1];
;                         w0[2] = v0[2] * a[2] - v0[3] * a[3]; w0[3] = v0[3] * a[2] + v0[2] * a[3];
;                         w1[0] = v1[0] * b[0] - v1[1] * b[1]; w1[1] = v1[1] * b[0] + v1[0] * b[1];
;                         w1[2] = v1[2] * b[2] - v1[3] * b[3]; w1[3] = v1[3] * b[2] + v1[2] * b[3];
;                         v0 = w0; v1 = w1;
.LBB0_363:
	s_andn2_b64 vcc, exec, s[0:1]
	s_cbranch_vccnz .LBB0_367
	s_cmp_eq_u32 s61, 1
	s_cbranch_scc0 .LBB0_366
	v_mov_b32_e32 v12, v232
	v_mov_b32_e32 v13, v233
	v_mov_b32_e32 v14, v234
	v_mov_b32_e32 v15, v235
	v_mov_b32_e32 v16, v236
	v_mov_b32_e32 v17, v237
	v_mov_b32_e32 v18, v238
	v_mov_b32_e32 v19, v239
	v_pk_mul_f32 v[24:25], v[2:3], v[12:13] op_sel:[1,1] op_sel_hi:[0,1]
	v_pk_mul_f32 v[22:23], v[6:7], v[16:17] op_sel:[1,1] op_sel_hi:[0,1]
	v_mul_f32_e32 v0, v9, v19
	v_pk_mul_f32 v[20:21], v[6:7], v[16:17]
	v_pk_fma_f32 v[6:7], v[6:7], v[16:17], v[22:23] op_sel_hi:[1,0,1]
	v_pk_fma_f32 v[16:17], v[8:9], v[18:19], v[0:1] op_sel_hi:[1,1,0] neg_lo:[0,0,1] neg_hi:[0,0,1]
	v_mul_f32_e32 v0, v8, v19
	v_pk_fma_f32 v[8:9], v[8:9], v[18:19], v[0:1] op_sel:[1,0,0] op_sel_hi:[0,1,0]
	v_mul_f32_e32 v0, v5, v15
	v_pk_mul_f32 v[18:19], v[2:3], v[12:13]
	v_pk_fma_f32 v[2:3], v[2:3], v[12:13], v[24:25] op_sel_hi:[1,0,1]
	v_pk_fma_f32 v[12:13], v[4:5], v[14:15], v[0:1] op_sel_hi:[1,1,0] neg_lo:[0,0,1] neg_hi:[0,0,1]
	v_mul_f32_e32 v0, v4, v15
	v_pk_fma_f32 v[4:5], v[4:5], v[14:15], v[0:1] op_sel:[1,0,0] op_sel_hi:[0,1,0]
	v_sub_f32_e32 v2, v18, v24
	v_sub_f32_e32 v6, v20, v22
	v_mov_b32_e32 v9, v8
	v_mov_b32_e32 v8, v16
	v_mov_b32_e32 v5, v4
	v_mov_b32_e32 v4, v12
